# GLU K-loop: one dword touch per 128-B line of the unit's epilogue operand tiles (gate plane, y_b plane) four iterations before the loop ends
# speedup vs baseline: 1.0010x; 1.0002x over previous
.LBB0_558:
	ds_read_b128 v[40:43], v228
	ds_read_b128 v[44:47], v228 offset:1024
	ds_read_b128 v[52:55], v228 offset:2048
	ds_read_b128 v[60:63], v228 offset:3072
	s_add_u32 s3, s10, 0xfff80080
	s_addc_u32 s28, s11, -1
	s_cmp_eq_u32 s84, s86
	s_cselect_b32 s35, s41, s28
	s_cselect_b32 s34, s43, s3
	s_cselect_b32 s29, s39, s85
	s_cselect_b32 s28, s50, s51
	v_lshl_add_u64 v[198:199], s[10:11], 0, v[192:193]
	s_add_i32 m0, s61, 0xc000
	ds_read_b128 v[144:147], v229
	ds_read_b128 v[148:151], v229 offset:1024
	ds_read_b128 v[152:155], v229 offset:2048
	ds_read_b128 v[156:159], v229 offset:3072
	ds_read_b128 v[160:163], v229 offset:4096
	ds_read_b128 v[164:167], v229 offset:5120
	ds_read_b128 v[168:171], v229 offset:6144
	ds_read_b128 v[172:175], v229 offset:7168
	global_load_lds_dwordx4 v[198:199], off
	v_lshl_add_u64 v[198:199], s[10:11], 0, v[194:195]
	s_add_i32 m0, s61, 0xe000
	s_nop 0
	global_load_lds_dwordx4 v[198:199], off
	s_waitcnt lgkmcnt(8)
	s_barrier
	s_waitcnt lgkmcnt(0)
	v_mfma_f32_16x16x32_bf16 v[140:143], v[40:43], v[144:147], v[140:143]
	v_mfma_f32_16x16x32_bf16 v[136:139], v[52:55], v[144:147], v[136:139]
	v_mfma_f32_16x16x32_bf16 v[124:127], v[40:43], v[152:155], v[124:127]
	v_mfma_f32_16x16x32_bf16 v[120:123], v[52:55], v[152:155], v[120:123]
	v_mfma_f32_16x16x32_bf16 v[108:111], v[40:43], v[160:163], v[108:111]
	v_mfma_f32_16x16x32_bf16 v[104:107], v[52:55], v[160:163], v[104:107]
	v_mfma_f32_16x16x32_bf16 v[92:95], v[40:43], v[168:171], v[92:95]
	v_mfma_f32_16x16x32_bf16 v[88:91], v[52:55], v[168:171], v[88:91]
	v_mfma_f32_16x16x32_bf16 v[140:143], v[44:47], v[148:151], v[140:143]
	v_mfma_f32_16x16x32_bf16 v[136:139], v[60:63], v[148:151], v[136:139]
	v_mfma_f32_16x16x32_bf16 v[124:127], v[44:47], v[156:159], v[124:127]
	v_mfma_f32_16x16x32_bf16 v[120:123], v[60:63], v[156:159], v[120:123]
	v_mfma_f32_16x16x32_bf16 v[108:111], v[44:47], v[164:167], v[108:111]
	v_mfma_f32_16x16x32_bf16 v[104:107], v[60:63], v[164:167], v[104:107]
	v_mfma_f32_16x16x32_bf16 v[92:95], v[44:47], v[172:175], v[92:95]
	v_mfma_f32_16x16x32_bf16 v[88:91], v[60:63], v[172:175], v[88:91]
	s_barrier
	s_add_i32 s3, s79, s69
	v_lshl_add_u64 v[236:237], s[28:29], 0, v[184:185]
	s_mov_b32 m0, s3
	ds_read_b128 v[198:201], v230
	ds_read_b128 v[202:205], v230 offset:1024
	ds_read_b128 v[206:209], v230 offset:2048
	ds_read_b128 v[232:235], v230 offset:3072
	global_load_lds_dwordx4 v[236:237], off
	v_lshl_add_u64 v[238:239], s[28:29], 0, v[188:189]
	s_add_i32 m0, s3, 0x2000
	s_nop 0
	global_load_lds_dwordx4 v[238:239], off
	s_barrier
	s_waitcnt lgkmcnt(0)
	v_mfma_f32_16x16x32_bf16 v[132:135], v[198:201], v[144:147], v[132:135]
	v_mfma_f32_16x16x32_bf16 v[128:131], v[206:209], v[144:147], v[128:131]
	v_mfma_f32_16x16x32_bf16 v[116:119], v[198:201], v[152:155], v[116:119]
	v_mfma_f32_16x16x32_bf16 v[112:115], v[206:209], v[152:155], v[112:115]
	v_mfma_f32_16x16x32_bf16 v[100:103], v[198:201], v[160:163], v[100:103]
	v_mfma_f32_16x16x32_bf16 v[96:99], v[206:209], v[160:163], v[96:99]
	v_mfma_f32_16x16x32_bf16 v[84:87], v[198:201], v[168:171], v[84:87]
	v_mfma_f32_16x16x32_bf16 v[80:83], v[206:209], v[168:171], v[80:83]
	v_mfma_f32_16x16x32_bf16 v[132:135], v[202:205], v[148:151], v[132:135]
	v_mfma_f32_16x16x32_bf16 v[128:131], v[232:235], v[148:151], v[128:131]
	v_mfma_f32_16x16x32_bf16 v[116:119], v[202:205], v[156:159], v[116:119]
	v_mfma_f32_16x16x32_bf16 v[112:115], v[232:235], v[156:159], v[112:115]
	v_mfma_f32_16x16x32_bf16 v[100:103], v[202:205], v[164:167], v[100:103]
	v_mfma_f32_16x16x32_bf16 v[96:99], v[232:235], v[164:167], v[96:99]
	v_mfma_f32_16x16x32_bf16 v[84:87], v[202:205], v[172:175], v[84:87]
	v_mfma_f32_16x16x32_bf16 v[80:83], v[232:235], v[172:175], v[80:83]
	s_mov_b32 m0, s61
	v_lshl_add_u64 v[240:241], s[34:35], 0, v[182:183]
	s_barrier
	ds_read_b128 v[144:147], v229 offset:16384
	ds_read_b128 v[148:151], v229 offset:17408
	ds_read_b128 v[152:155], v229 offset:18432
	ds_read_b128 v[156:159], v229 offset:19456
	ds_read_b128 v[160:163], v229 offset:20480
	ds_read_b128 v[164:167], v229 offset:21504
	ds_read_b128 v[168:171], v229 offset:22528
	ds_read_b128 v[172:175], v229 offset:23552
	global_load_lds_dwordx4 v[240:241], off
	v_lshl_add_u64 v[242:243], s[34:35], 0, v[186:187]
	s_mov_b32 m0, s63
	s_nop 0
	global_load_lds_dwordx4 v[242:243], off
	s_barrier
	s_waitcnt lgkmcnt(0)
	v_mfma_f32_16x16x32_bf16 v[76:79], v[40:43], v[144:147], v[76:79]
	v_mfma_f32_16x16x32_bf16 v[72:75], v[52:55], v[144:147], v[72:75]
	v_mfma_f32_16x16x32_bf16 v[56:59], v[40:43], v[152:155], v[56:59]
	v_mfma_f32_16x16x32_bf16 v[48:51], v[52:55], v[152:155], v[48:51]
	v_mfma_f32_16x16x32_bf16 v[28:31], v[40:43], v[160:163], v[28:31]
	v_mfma_f32_16x16x32_bf16 v[24:27], v[52:55], v[160:163], v[24:27]
	v_mfma_f32_16x16x32_bf16 v[12:15], v[40:43], v[168:171], v[12:15]
	v_mfma_f32_16x16x32_bf16 v[8:11], v[52:55], v[168:171], v[8:11]
	v_mfma_f32_16x16x32_bf16 v[76:79], v[44:47], v[148:151], v[76:79]
	v_mfma_f32_16x16x32_bf16 v[72:75], v[60:63], v[148:151], v[72:75]
	v_mfma_f32_16x16x32_bf16 v[56:59], v[44:47], v[156:159], v[56:59]
	v_mfma_f32_16x16x32_bf16 v[48:51], v[60:63], v[156:159], v[48:51]
	v_mfma_f32_16x16x32_bf16 v[28:31], v[44:47], v[164:167], v[28:31]
	v_mfma_f32_16x16x32_bf16 v[24:27], v[60:63], v[164:167], v[24:27]
	v_mfma_f32_16x16x32_bf16 v[12:15], v[44:47], v[172:175], v[12:15]
	v_mfma_f32_16x16x32_bf16 v[8:11], v[60:63], v[172:175], v[8:11]
	s_barrier
	s_add_u32 s88, s28, 0x80000
	s_addc_u32 s89, s29, 0
	s_add_i32 s3, s80, s69
	v_lshl_add_u64 v[40:41], s[88:89], 0, v[184:185]
	s_mov_b32 m0, s3
	s_nop 0
	global_load_lds_dwordx4 v[40:41], off
	v_lshl_add_u64 v[40:41], s[88:89], 0, v[188:189]
	s_add_i32 m0, s3, 0x2000
	s_nop 0
	global_load_lds_dwordx4 v[40:41], off
	s_cmp_eq_u32 s86, 26
	s_cbranch_scc1 .Lpf_glu
	s_waitcnt vmcnt(6)
.Lpf_glu_back:
	s_barrier
	v_mfma_f32_16x16x32_bf16 v[36:39], v[198:201], v[152:155], v[36:39]
	v_mfma_f32_16x16x32_bf16 v[32:35], v[206:209], v[152:155], v[32:35]
	v_mfma_f32_16x16x32_bf16 v[20:23], v[198:201], v[160:163], v[20:23]
	v_mfma_f32_16x16x32_bf16 v[16:19], v[206:209], v[160:163], v[16:19]
	v_mfma_f32_16x16x32_bf16 v[4:7], v[198:201], v[168:171], v[4:7]
	v_mfma_f32_16x16x32_bf16 v[0:3], v[206:209], v[168:171], v[0:3]
	v_mfma_f32_16x16x32_bf16 v[40:43], v[198:201], v[144:147], v[68:71]
	v_mfma_f32_16x16x32_bf16 v[44:47], v[206:209], v[144:147], v[64:67]
	v_mfma_f32_16x16x32_bf16 v[36:39], v[202:205], v[156:159], v[36:39]
	v_mfma_f32_16x16x32_bf16 v[32:35], v[232:235], v[156:159], v[32:35]
	v_mfma_f32_16x16x32_bf16 v[20:23], v[202:205], v[164:167], v[20:23]
	v_mfma_f32_16x16x32_bf16 v[16:19], v[232:235], v[164:167], v[16:19]
	v_mfma_f32_16x16x32_bf16 v[4:7], v[202:205], v[172:175], v[4:7]
	v_mfma_f32_16x16x32_bf16 v[0:3], v[232:235], v[172:175], v[0:3]
	v_mfma_f32_16x16x32_bf16 v[40:43], v[202:205], v[148:151], v[40:43]
	v_mfma_f32_16x16x32_bf16 v[44:47], v[232:235], v[148:151], v[44:47]
	s_add_i32 s3, 0, 0x18000
	v_add_u32_e32 v68, s3, v226
	s_barrier
	ds_read_b128 v[52:55], v68
	ds_read_b128 v[60:63], v68 offset:1024
	ds_read_b128 v[64:67], v68 offset:2048
	ds_read_b128 v[68:71], v68 offset:3072
	s_add_u32 s34, s34, 0x80000
	s_addc_u32 s35, s35, 0
	s_mov_b32 m0, s67
	v_lshl_add_u64 v[198:199], s[34:35], 0, v[182:183]
	ds_read_b128 v[144:147], v229 offset:32768
	ds_read_b128 v[148:151], v229 offset:33792
	ds_read_b128 v[152:155], v229 offset:34816
	ds_read_b128 v[156:159], v229 offset:35840
	ds_read_b128 v[160:163], v229 offset:36864
	ds_read_b128 v[164:167], v229 offset:37888
	ds_read_b128 v[168:171], v229 offset:38912
	ds_read_b128 v[172:175], v229 offset:39936
	global_load_lds_dwordx4 v[198:199], off
	v_lshl_add_u64 v[198:199], s[34:35], 0, v[186:187]
	s_mov_b32 m0, s70
	s_nop 0
	global_load_lds_dwordx4 v[198:199], off
	s_waitcnt lgkmcnt(8)
	s_barrier
	s_waitcnt lgkmcnt(0)
	v_mfma_f32_16x16x32_bf16 v[140:143], v[52:55], v[144:147], v[140:143]
	v_mfma_f32_16x16x32_bf16 v[136:139], v[64:67], v[144:147], v[136:139]
	v_mfma_f32_16x16x32_bf16 v[124:127], v[52:55], v[152:155], v[124:127]
	v_mfma_f32_16x16x32_bf16 v[120:123], v[64:67], v[152:155], v[120:123]
	v_mfma_f32_16x16x32_bf16 v[108:111], v[52:55], v[160:163], v[108:111]
	v_mfma_f32_16x16x32_bf16 v[104:107], v[64:67], v[160:163], v[104:107]
	v_mfma_f32_16x16x32_bf16 v[92:95], v[52:55], v[168:171], v[92:95]
	v_mfma_f32_16x16x32_bf16 v[88:91], v[64:67], v[168:171], v[88:91]
	v_mfma_f32_16x16x32_bf16 v[140:143], v[60:63], v[148:151], v[140:143]
	v_mfma_f32_16x16x32_bf16 v[136:139], v[68:71], v[148:151], v[136:139]
	v_mfma_f32_16x16x32_bf16 v[124:127], v[60:63], v[156:159], v[124:127]
	v_mfma_f32_16x16x32_bf16 v[120:123], v[68:71], v[156:159], v[120:123]
	v_mfma_f32_16x16x32_bf16 v[108:111], v[60:63], v[164:167], v[108:111]
	v_mfma_f32_16x16x32_bf16 v[104:107], v[68:71], v[164:167], v[104:107]
	v_mfma_f32_16x16x32_bf16 v[92:95], v[60:63], v[172:175], v[92:95]
	v_mfma_f32_16x16x32_bf16 v[88:91], v[68:71], v[172:175], v[88:91]
	s_barrier
	s_add_i32 s34, 0, 0x1c000
	s_add_i32 s3, s3, s69
	v_add_u32_e32 v231, s34, v226
	v_lshl_add_u64 v[236:237], v[236:237], 0, s[22:23]
	s_mov_b32 m0, s3
	ds_read_b128 v[198:201], v231
	ds_read_b128 v[202:205], v231 offset:1024
	ds_read_b128 v[206:209], v231 offset:2048
	ds_read_b128 v[232:235], v231 offset:3072
	global_load_lds_dwordx4 v[236:237], off
	v_lshl_add_u64 v[236:237], v[238:239], 0, s[22:23]
	s_add_i32 m0, s3, 0x2000
	s_nop 0
	global_load_lds_dwordx4 v[236:237], off
	s_barrier
	s_waitcnt lgkmcnt(0)
	v_mfma_f32_16x16x32_bf16 v[132:135], v[198:201], v[144:147], v[132:135]
	v_mfma_f32_16x16x32_bf16 v[128:131], v[206:209], v[144:147], v[128:131]
	v_mfma_f32_16x16x32_bf16 v[116:119], v[198:201], v[152:155], v[116:119]
	v_mfma_f32_16x16x32_bf16 v[112:115], v[206:209], v[152:155], v[112:115]
	v_mfma_f32_16x16x32_bf16 v[100:103], v[198:201], v[160:163], v[100:103]
	v_mfma_f32_16x16x32_bf16 v[96:99], v[206:209], v[160:163], v[96:99]
	v_mfma_f32_16x16x32_bf16 v[84:87], v[198:201], v[168:171], v[84:87]
	v_mfma_f32_16x16x32_bf16 v[80:83], v[206:209], v[168:171], v[80:83]
	v_mfma_f32_16x16x32_bf16 v[132:135], v[202:205], v[148:151], v[132:135]
	v_mfma_f32_16x16x32_bf16 v[128:131], v[232:235], v[148:151], v[128:131]
	v_mfma_f32_16x16x32_bf16 v[116:119], v[202:205], v[156:159], v[116:119]
	v_mfma_f32_16x16x32_bf16 v[112:115], v[232:235], v[156:159], v[112:115]
	v_mfma_f32_16x16x32_bf16 v[100:103], v[202:205], v[164:167], v[100:103]
	v_mfma_f32_16x16x32_bf16 v[96:99], v[232:235], v[164:167], v[96:99]
	v_mfma_f32_16x16x32_bf16 v[84:87], v[202:205], v[172:175], v[84:87]
	v_mfma_f32_16x16x32_bf16 v[80:83], v[232:235], v[172:175], v[80:83]
	s_mov_b32 m0, s71
	v_lshl_add_u64 v[236:237], v[240:241], 0, s[22:23]
	s_barrier
	ds_read_b128 v[144:147], v229 offset:49152
	ds_read_b128 v[148:151], v229 offset:50176
	ds_read_b128 v[152:155], v229 offset:51200
	ds_read_b128 v[156:159], v229 offset:52224
	ds_read_b128 v[160:163], v229 offset:53248
	ds_read_b128 v[164:167], v229 offset:54272
	ds_read_b128 v[168:171], v229 offset:55296
	ds_read_b128 v[172:175], v229 offset:56320
	global_load_lds_dwordx4 v[236:237], off
	v_lshl_add_u64 v[236:237], v[242:243], 0, s[22:23]
	s_mov_b32 m0, s74
	s_nop 0
	global_load_lds_dwordx4 v[236:237], off
	s_barrier
	s_waitcnt lgkmcnt(0)
	v_mfma_f32_16x16x32_bf16 v[76:79], v[52:55], v[144:147], v[76:79]
	v_mfma_f32_16x16x32_bf16 v[72:75], v[64:67], v[144:147], v[72:75]
	v_mfma_f32_16x16x32_bf16 v[56:59], v[52:55], v[152:155], v[56:59]
	v_mfma_f32_16x16x32_bf16 v[48:51], v[64:67], v[152:155], v[48:51]
	v_mfma_f32_16x16x32_bf16 v[28:31], v[52:55], v[160:163], v[28:31]
	v_mfma_f32_16x16x32_bf16 v[24:27], v[64:67], v[160:163], v[24:27]
	v_mfma_f32_16x16x32_bf16 v[12:15], v[52:55], v[168:171], v[12:15]
	v_mfma_f32_16x16x32_bf16 v[8:11], v[64:67], v[168:171], v[8:11]
	v_mfma_f32_16x16x32_bf16 v[76:79], v[60:63], v[148:151], v[76:79]
	v_mfma_f32_16x16x32_bf16 v[72:75], v[68:71], v[148:151], v[72:75]
	v_mfma_f32_16x16x32_bf16 v[56:59], v[60:63], v[156:159], v[56:59]
	v_mfma_f32_16x16x32_bf16 v[48:51], v[68:71], v[156:159], v[48:51]
	v_mfma_f32_16x16x32_bf16 v[28:31], v[60:63], v[164:167], v[28:31]
	v_mfma_f32_16x16x32_bf16 v[24:27], v[68:71], v[164:167], v[24:27]
	v_mfma_f32_16x16x32_bf16 v[12:15], v[60:63], v[172:175], v[12:15]
	v_mfma_f32_16x16x32_bf16 v[8:11], v[68:71], v[172:175], v[8:11]
	s_barrier
	s_add_u32 s28, s28, 0x80080
	s_addc_u32 s29, s29, 0
	s_add_i32 s3, s34, s69
	v_lshl_add_u64 v[52:53], s[28:29], 0, v[184:185]
	s_mov_b32 m0, s3
	s_nop 0
	global_load_lds_dwordx4 v[52:53], off
	v_lshl_add_u64 v[52:53], s[28:29], 0, v[188:189]
	s_add_i32 m0, s3, 0x2000
	s_nop 0
	global_load_lds_dwordx4 v[52:53], off
	s_waitcnt vmcnt(6)
	s_barrier
	v_mfma_f32_16x16x32_bf16 v[40:43], v[198:201], v[144:147], v[40:43]
	v_mfma_f32_16x16x32_bf16 v[68:71], v[202:205], v[148:151], v[40:43]
	v_mfma_f32_16x16x32_bf16 v[40:43], v[206:209], v[144:147], v[44:47]
	v_mfma_f32_16x16x32_bf16 v[36:39], v[198:201], v[152:155], v[36:39]
	v_mfma_f32_16x16x32_bf16 v[32:35], v[206:209], v[152:155], v[32:35]
	v_mfma_f32_16x16x32_bf16 v[20:23], v[198:201], v[160:163], v[20:23]
	v_mfma_f32_16x16x32_bf16 v[16:19], v[206:209], v[160:163], v[16:19]
	v_mfma_f32_16x16x32_bf16 v[4:7], v[198:201], v[168:171], v[4:7]
	v_mfma_f32_16x16x32_bf16 v[0:3], v[206:209], v[168:171], v[0:3]
	v_mfma_f32_16x16x32_bf16 v[64:67], v[232:235], v[148:151], v[40:43]
	v_mfma_f32_16x16x32_bf16 v[36:39], v[202:205], v[156:159], v[36:39]
	v_mfma_f32_16x16x32_bf16 v[32:35], v[232:235], v[156:159], v[32:35]
	v_mfma_f32_16x16x32_bf16 v[20:23], v[202:205], v[164:167], v[20:23]
	v_mfma_f32_16x16x32_bf16 v[16:19], v[232:235], v[164:167], v[16:19]
	v_mfma_f32_16x16x32_bf16 v[4:7], v[202:205], v[172:175], v[4:7]
	v_mfma_f32_16x16x32_bf16 v[0:3], v[232:235], v[172:175], v[0:3]
	s_add_i32 s3, s86, 2
	s_add_u32 s10, s10, 0x100
	s_addc_u32 s11, s11, 0
	s_add_u32 s51, s51, 0x100
	s_addc_u32 s85, s85, 0
	s_cmp_ge_u32 s86, s84
	s_mov_b32 s86, s3
	s_barrier
	s_cbranch_scc0 .LBB0_558

.Lpf_glu:
	v_and_b32_e32 v244, 64, v225
	v_and_b32_e32 v245, 0x60, v227
	v_lshl_add_u32 v244, v244, 1, v245
	v_and_b32_e32 v245, 15, v225
	v_add_u32_e32 v244, v244, v245
	s_lshl_b32 s3, s60, 8
	v_add_u32_e32 v244, s3, v244
	v_lshlrev_b32_e32 v244, 12, v244
	v_and_b32_e32 v245, 24, v227
	v_lshl_add_u32 v244, v245, 4, v244
	s_lshl_b32 s3, s62, 9
	v_add_u32_e32 v244, s3, v244
	v_add_u32_e32 v245, 0x10000, v244
	global_load_dword v246, v244, s[6:7]
	global_load_dword v247, v245, s[6:7]
	global_load_dword v248, v244, s[8:9]
	global_load_dword v249, v245, s[8:9]
	s_waitcnt vmcnt(10)
	s_branch .Lpf_glu_back
